# diff attention: LDS-DMA issue moved behind the K-fragment ds_reads (hidden in LDS latency); otherwise as v36
# baseline (speedup 1.0000x reference)
; template <int KIND> ...
;     ...
;     if (KIND == 2) { const float s01 = wave_sum(lam[lane] * lam[64 + lane]), s23 = wave_sum(lam[128 + lane] * lam[192 + lane]);
;         lam_full = __builtin_amdgcn_exp2f(s01 * LOG2E) - __builtin_amdgcn_exp2f(s23 * LOG2E) + lam_init; }
;     if (wid >= 4) __builtin_amdgcn_s_setprio(1);
;     const int n_units = 2048 + (do_ctx ? 128 : 0);
;     for (int u = blockIdx.x; u < n_units; u += gridDim.x) {
;         const bool isctx = u >= 2048; const int uu = isctx ? u - 2048 : u;
;         int b, h, qb;
;         const int xw = uu & 7, jw = (uu >> 3) & 31;
;         if (KIND == 2) { if (!isctx) { qb = jw; h = xw; b = uu >> 8; } else { qb = uu & 1; h = (uu >> 1) & 7; b = uu >> 4; } }
;         else if (KIND == 1) { if (!isctx) { const int item = (xw >> 2) * 32 + jw; qb = item & 15; h = (xw & 3) * 4 + (item >> 4); b = uu >> 8; } else { qb = 0; h = uu & 15; b = uu >> 4; } }
;         else           { if (!isctx) { qb = jw & 15; h = xw + 8 * (jw >> 4); b = uu >> 8; } else { qb = 0; h = uu & 15; b = uu >> 4; } }
;         const int qrow0 = isctx ? M_LAT + b * 256 + qb * QW : b * 4096 + qb * QW;
;         int qoff, hq, kidx;
;         if (KIND == 2) { const int i = wid >> 2; qoff = 32 * (wid & 3); hq = i * 8 + h; kidx = i; } else { qoff = 32 * wid; hq = h; kidx = 0; }
;         const int kcol0 = KIND == 1 ? 1024 + (h >> 2) * 64 : 1024 + h * 64;
;         const int vcol = KIND == 0 ? 2048 + h * 64 : (KIND == 1 ? 1280 + (h >> 2) * 64 : 2048 + h * 128);
;         int base1 = b * 4096, n1 = 64, kr_lo = 0, rs_w = 0, qr = 0, qc = 0, cs = 0;
;         if (KIND == 0) { const int r0 = qb * 4; kr_lo = min(max(r0 - 4, 0), 56); const int kr_hi = min(max(r0 - 1, 0), 56) + 8; base1 += kr_lo * 64; n1 = kr_hi - kr_lo;
;             qr = r0 + (wid >> 1); rs_w = min(max(qr - 4, 0), 56); qc = 32 * (wid & 1) + l32; cs = min(max(qc - 8, 0), 48); }
;         if (isctx) n1 = 0;
;         const int base2 = M_LAT + b * 256, nt = n1 + 4;
;         bf16x8 qf[4];
;         { const bf16_t* qp = qkv + (size_t)(qrow0 + qoff + l32) * N + hq * 64 + 8 * hi;
; #pragma unroll
;           for (int t = 0; t < 4; ++t) qf[t] = *(const bf16x8*)(qp + 16 * t); }
;         if (KIND == 0 && !isctx) { LAS float* bt = (LAS float*)(lds + OFF_BIAS); for (int i = tid; i < 465; i += NTHREADS) bt[i] = rpb[h * 465 + i] * LOG2E; }
;         u32x4 kreg[NK], vreg[NVC];
.LBB0_176:
	s_and_b64 s[2:3], s[6:7], exec
	s_movk_i32 s2, 0x880
	s_cselect_b32 s20, s2, 0x800
	s_cmp_ge_i32 s74, s20
	s_cbranch_scc1 .LBB0_202
	s_waitcnt lgkmcnt(1)
	v_add_f32_e32 v0, v0, v1
	s_waitcnt lgkmcnt(0)
	v_add_f32_e32 v1, v2, v3
	v_mul_f32_e32 v0, 0x3fb8aa3b, v0
	v_mul_f32_e32 v1, 0x3fb8aa3b, v1
	v_exp_f32_e32 v0, v0
	v_exp_f32_e32 v1, v1
	v_ashrrev_i32_e32 v226, 3, v198
	v_ashrrev_i32_e32 v2, 5, v196
	v_mul_lo_u32 v3, v226, s90
	v_sub_f32_e32 v0, v0, v1
	v_and_b32_e32 v1, 7, v196
	v_lshlrev_b32_e32 v192, 4, v1
	v_bfe_u32 v4, v196, 2, 2
	v_lshlrev_b32_e32 v202, 3, v2
	v_add3_u32 v234, 0, v3, v192
	v_lshlrev_b32_e32 v3, 4, v2
	v_lshl_or_b32 v2, v2, 2, v4
	v_and_b32_e32 v4, 16, v196
	v_lshlrev_b32_e32 v5, 2, v196
	s_ashr_i32 s2, s38, 2
	s_movk_i32 s4, 0x140
	v_and_or_b32 v4, v5, 12, v4
	v_and_b32_e32 v199, 31, v196
	s_lshl_b32 s22, s2, 9
	s_mulk_i32 s2, 0x2400
	v_mul_lo_u32 v2, v2, s4
	v_lshlrev_b32_e32 v4, 1, v4
	v_add_f32_e32 v200, s19, v0
	v_lshlrev_b32_e32 v0, 3, v1
	v_mul_u32_u24_e32 v1, 0x90, v199
	s_add_i32 s2, s2, 0
	v_add3_u32 v236, 0, v2, v4
	v_add_u32_e32 v4, 0x200, v198
	v_add3_u32 v235, s2, v1, v3
	v_ashrrev_i32_e32 v1, 31, v198
	v_ashrrev_i32_e32 v5, 31, v4
	v_lshrrev_b32_e32 v1, 28, v1
	v_lshrrev_b32_e32 v5, 28, v5
	s_and_b32 s3, s38, 3
	v_add_u32_e32 v1, v198, v1
	v_add_u32_e32 v5, v4, v5
	s_lshl_b32 s2, s3, 14
	v_ashrrev_i32_e32 v237, 4, v1
	v_and_b32_e32 v1, -16, v1
	v_ashrrev_i32_e32 v238, 4, v5
	v_and_b32_e32 v5, -16, v5
	s_lshl_b32 s21, s3, 5
	s_add_i32 s23, s2, 0
	v_sub_u32_e32 v1, v198, v1
	v_sub_u32_e32 v6, v4, v5
	s_cmp_lt_i32 s38, 4
	s_mulk_i32 s3, 0x2200
	v_lshlrev_b32_e32 v2, 3, v1
	v_lshlrev_b32_e32 v4, 3, v6
	v_mul_lo_u32 v239, v237, s4
	v_mul_lo_u32 v241, v238, s4
	s_cselect_b64 s[12:13], -1, 0
	s_add_i32 s24, s3, 0
	v_ashrrev_i32_e32 v3, 31, v2
	v_ashrrev_i32_e32 v5, 31, v4
	v_add_u32_e32 v7, 0, v239
	v_lshlrev_b32_e32 v240, 4, v1
	v_add_u32_e32 v1, 0, v241
	v_lshlrev_b32_e32 v242, 4, v6
	v_ashrrev_i32_e32 v203, 31, v202
	v_lshl_add_u64 v[204:205], s[58:59], 0, v[192:193]
	s_add_i32 s24, s24, 0x14000
	v_mov_b32_e32 v201, v200
	v_add_u32_e32 v243, 0x80, v238
	v_add_u32_e32 v244, 0x80, v237
	v_add_u32_e32 v245, 0x80, v226
	v_lshlrev_b32_e32 v192, 1, v0
	v_lshlrev_b64 v[206:207], 1, v[2:3]
	v_lshlrev_b64 v[208:209], 1, v[4:5]
	v_add_u32_e32 v246, v7, v240
	v_add_u32_e32 v247, v1, v242
	v_bfe_u32 v8, v198, 4, 3
	v_and_b32_e32 v9, 7, v196
	v_xor_b32_e32 v8, v9, v8
	v_lshlrev_b32_e32 v192, 4, v8
	s_add_u32 s28, s58, 0x800
	s_addc_u32 s29, s59, 0
	v_lshl_add_u64 v[204:205], s[28:29], 0, v[192:193]
	v_and_b32_e32 v8, 15, v198
	v_bfe_u32 v9, v198, 4, 2
	v_lshlrev_b32_e32 v9, 2, v9
	v_xor_b32_e32 v8, v8, v9
	v_lshlrev_b32_e32 v206, 4, v8
	v_mov_b32_e32 v207, 0
	v_mov_b32_e32 v208, v206
	v_mov_b32_e32 v209, 0
	v_and_b32_e32 v8, 31, v196
	v_lshlrev_b32_e32 v8, 7, v8
	v_lshrrev_b32_e32 v9, 5, v196
	v_bfe_u32 v10, v196, 1, 1
	v_xor_b32_e32 v9, v9, v10
	v_lshl_or_b32 v8, v9, 4, v8
	v_bfe_u32 v9, v196, 2, 2
	v_lshl_or_b32 v8, v9, 5, v8
	s_ashr_i32 s28, s38, 2
	s_lshl_b32 s28, s28, 13
	v_add_u32_e32 v235, s28, v8
	v_lshrrev_b32_e32 v8, 5, v196
	v_bfe_u32 v9, v196, 2, 2
	v_lshl_or_b32 v8, v8, 2, v9
	v_lshlrev_b32_e32 v8, 8, v8
	v_lshl_or_b32 v8, v9, 6, v8
	v_bfe_u32 v9, v196, 4, 1
	v_lshl_or_b32 v8, v9, 5, v8
	v_and_b32_e32 v9, 3, v196
	v_lshl_or_b32 v236, v9, 3, v8
	s_lshl_b32 s18, s38, 10
	s_mov_b32 s25, s74
	s_branch .LBB0_179

; #define LAS __attribute__((address_space(3)))
; template <int KIND> ...
;     ...
;         { const bf16_t* qp = qkv + (size_t)(qrow0 + qoff + l32) * N + hq * 64 + 8 * hi;
; #pragma unroll
;           for (int t = 0; t < 4; ++t) qf[t] = *(const bf16x8*)(qp + 16 * t); }
;         if (KIND == 0 && !isctx) { LAS float* bt = (LAS float*)(lds + OFF_BIAS); for (int i = tid; i < 465; i += NTHREADS) bt[i] = rpb[h * 465 + i] * LOG2E; }
;         u32x4 kreg[NK], vreg[NVC];
;         const int krow_l = tid >> 3, kpart = tid & 7;
;     ...
;         float m_ref = 0.f; int first = 1;
;         f32x16 o[NDT], lacc, mneg;
; #pragma unroll
;         for (int dt = 0; dt < NDT; ++dt)
; #pragma unroll
;             for (int j = 0; j < 16; ++j) o[dt][j] = 0.f;
; #pragma unroll
;         for (int j = 0; j < 16; ++j) { lacc[j] = 0.f; mneg[j] = 0.f; }
;         const bf16x8 ones = {(short)0x3F80, (short)0x3F80, (short)0x3F80, (short)0x3F80, (short)0x3F80, (short)0x3F80, (short)0x3F80, (short)0x3F80};
;         ATT_LOAD(0); ATT_STORE(0); __syncthreads();
;         const int koff = kidx * KT + l32 * KSTR + 16 * hi;
;         const int voff = OFF_V + (4 * hi + ((lane & 15) >> 2)) * VSTR + (16 * ((lane >> 4) & 1) + 4 * (lane & 3)) * 2;
;         const int wb = 4 * hi - cs;
;         const int boff0 = OFF_BIAS + 4 * (cs - qc + 15 + wb);
;         for (int t = 0; t < nt; ++t) {
;             if (t + 1 < nt) ATT_LOAD(t + 1);
;             bool active = true;
;             if (KIND == 0 && t < n1) { const int kr = kr_lo + t; active = (kr >= rs_w) && (kr < rs_w + 8); }
;             if (__builtin_amdgcn_readfirstlane((int)active)) {
;                 const int buf = t & 1;
;                 bf16x8 kf[8];
; #pragma unroll
;                 for (int t4 = 0; t4 < 4; ++t4) { kf[2 * t4] = *(const LAS bf16x8*)(lds + buf * KBUF + koff + 32 * t4); kf[2 * t4 + 1] = *(const LAS bf16x8*)(lds + buf * KBUF + koff + 32 * KSTR + 32 * t4); }
;                 __builtin_amdgcn_sched_barrier(0);
;                 f32x16 s0, s1;
; #pragma unroll
;                 for (int t4 = 0; t4 < 4; ++t4) {
;                     s0 = __builtin_amdgcn_mfma_f32_32x32x16_bf16(kf[2 * t4], qf[t4], t4 == 0 ? mneg : s0, 0, 0, 0);
;                     s1 = __builtin_amdgcn_mfma_f32_32x32x16_bf16(kf[2 * t4 + 1], qf[t4], t4 == 0 ? mneg : s1, 0, 0, 0);
;                 }
;     ...
;                 const float mx0 = fmaxf(s1[15], s0[15]);
.LBB0_187:
	s_add_i32 s14, s14, s21
	s_and_b32 s26, s26, 7
	v_add_u32_e32 v2, s14, v199
	v_mov_b64_e32 v[0:1], s[58:59]
	s_movk_i32 s34, 0x1800
	s_lshl_b32 s28, s26, 6
	v_mad_i64_i32 v[2:3], s[4:5], v2, s34, v[0:1]
	s_or_b32 s4, s28, s22
	s_lshl_b32 s96, s26, 7
	s_add_i32 s15, s27, 0x8000
	s_ashr_i32 s5, s4, 31
	v_lshl_add_u64 v[2:3], s[4:5], 1, v[2:3]
	s_and_b64 s[4:5], s[16:17], exec
	v_lshl_add_u64 v[2:3], v[202:203], 1, v[2:3]
	s_cselect_b32 s30, s2, s15
	global_load_dwordx4 v[128:131], v[2:3], off
	global_load_dwordx4 v[132:135], v[2:3], off offset:32
	global_load_dwordx4 v[136:139], v[2:3], off offset:64
	global_load_dwordx4 v[140:143], v[2:3], off offset:96
	s_lshl_b32 s4, s26, 8
	s_add_u32 s4, s58, s4
	s_addc_u32 s5, s59, 0
	s_add_u32 s4, s4, 0x1000
	s_addc_u32 s5, s5, 0
	v_lshl_add_u64 v[210:211], v[204:205], 0, s[96:97]
	v_mov_b64_e32 v[16:17], s[4:5]
	s_or_b32 s26, s3, 4
	s_or_b32 s28, s2, 64
	s_add_i32 s27, s27, 0x8040
	s_and_b64 s[16:17], s[16:17], exec
	s_cselect_b32 s27, s28, s27
	v_add_u32_e32 v0, s30, v226
	v_mad_i64_i32 v[0:1], vcc, v0, s34, v[210:211]
	s_mov_b32 m0, s18
	v_add_u32_e32 v2, s30, v237
	global_load_lds_dwordx4 v[0:1], off
	s_add_i32 m0, s18, 0x1c00
	v_mad_i64_i32 v[2:3], vcc, v2, s34, v[16:17]
	global_load_lds_dwordx4 v[0:1], off offset:1024
	v_lshl_add_u64 v[2:3], v[2:3], 0, v[206:207]
	s_add_i32 m0, s18, 0x8000
	v_add_u32_e32 v4, s30, v238
	global_load_lds_dwordx4 v[2:3], off
	v_mad_i64_i32 v[4:5], vcc, v4, s34, v[16:17]
	v_lshl_add_u64 v[4:5], v[4:5], 0, v[208:209]
	s_add_i32 m0, s18, 0xa000
	s_nop 0
	global_load_lds_dwordx4 v[4:5], off
	s_waitcnt vmcnt(0)
	s_barrier
	v_add_u32_e32 v0, s27, v226
	v_mad_i64_i32 v[0:1], vcc, v0, s34, v[210:211]
	s_add_i32 m0, s18, 0x4000
	v_add_u32_e32 v2, s27, v237
	global_load_lds_dwordx4 v[0:1], off
	s_add_i32 m0, s18, 0x5c00
	v_mad_i64_i32 v[2:3], vcc, v2, s34, v[16:17]
	global_load_lds_dwordx4 v[0:1], off offset:1024
	v_lshl_add_u64 v[2:3], v[2:3], 0, v[206:207]
	s_add_i32 m0, s18, 0xc000
	v_add_u32_e32 v4, s27, v238
	global_load_lds_dwordx4 v[2:3], off
	v_mad_i64_i32 v[4:5], vcc, v4, s34, v[16:17]
	v_lshl_add_u64 v[4:5], v[4:5], 0, v[208:209]
	s_add_i32 m0, s18, 0xe000
	s_nop 0
	global_load_lds_dwordx4 v[4:5], off
	v_xor_b32_e32 v144, 32, v235
	v_xor_b32_e32 v145, 64, v235
	v_xor_b32_e32 v146, 0x60, v235
	v_xor_b32_e32 v147, 64, v236
	v_xor_b32_e32 v148, 0x80, v236
	v_xor_b32_e32 v149, 0xc0, v236
	ds_read_b128 v[16:19], v235 offset:4096
	ds_read_b128 v[0:3], v235
	ds_read_b128 v[32:35], v144
	ds_read_b128 v[36:39], v144 offset:4096
	ds_read_b128 v[40:43], v145
	ds_read_b128 v[44:47], v145 offset:4096
	ds_read_b128 v[48:51], v146
	ds_read_b128 v[52:55], v146 offset:4096
	s_waitcnt lgkmcnt(6)
	v_mfma_f32_32x32x16_bf16 v[0:15], v[0:3], v[128:131], 0
	ds_read_b64_tr_b16 v[112:113], v148 offset:32768
	ds_read_b64_tr_b16 v[116:117], v149 offset:32768
	ds_read_b64_tr_b16 v[114:115], v148 offset:34816
	ds_read_b64_tr_b16 v[118:119], v149 offset:34816
	ds_read_b64_tr_b16 v[108:109], v236 offset:36864
	ds_read_b64_tr_b16 v[104:105], v147 offset:36864
	ds_read_b64_tr_b16 v[100:101], v148 offset:36864
	v_mfma_f32_32x32x16_bf16 v[16:31], v[16:19], v[128:131], 0
	ds_read_b64_tr_b16 v[96:97], v149 offset:36864
	ds_read_b64_tr_b16 v[110:111], v236 offset:38912
	ds_read_b64_tr_b16 v[106:107], v147 offset:38912
	ds_read_b64_tr_b16 v[102:103], v148 offset:38912
	ds_read_b64_tr_b16 v[98:99], v149 offset:38912
	s_waitcnt lgkmcnt(14)
	v_mfma_f32_32x32x16_bf16 v[0:15], v[32:35], v[132:135], v[0:15]
	ds_read_b64_tr_b16 v[32:33], v236 offset:32768
	ds_read_b64_tr_b16 v[34:35], v236 offset:34816
	v_mfma_f32_32x32x16_bf16 v[16:31], v[36:39], v[132:135], v[16:31]
	ds_read_b64_tr_b16 v[36:37], v147 offset:32768
	ds_read_b64_tr_b16 v[38:39], v147 offset:34816
	v_mfma_f32_32x32x16_bf16 v[0:15], v[40:43], v[136:139], v[0:15]
	v_mfma_f32_32x32x16_bf16 v[16:31], v[44:47], v[136:139], v[16:31]
	s_waitcnt lgkmcnt(14)
	v_mfma_f32_32x32x16_bf16 v[0:15], v[48:51], v[140:143], v[0:15]
	v_mfma_f32_32x32x16_bf16 v[16:31], v[52:55], v[140:143], v[16:31]
	s_nop 10
	v_max_f32_e32 v40, v15, v15
	v_max_f32_e32 v41, v31, v31
	v_max_f32_e32 v40, v41, v40
	v_max3_f32 v41, v40, v0, v16
	v_max3_f32 v40, v40, v1, v17
	s_nop 0
	v_max3_f32 v41, v41, v2, v18
	v_max3_f32 v40, v40, v3, v19
	s_nop 0
	v_max3_f32 v41, v41, v4, v20
	v_max3_f32 v40, v40, v5, v21
	s_nop 0
	v_max3_f32 v41, v41, v6, v22
	v_max3_f32 v40, v40, v7, v23
	s_nop 0
	v_max3_f32 v41, v41, v8, v24
	v_max3_f32 v40, v40, v9, v25
	s_nop 0
	v_max3_f32 v41, v41, v10, v26
	v_max3_f32 v40, v40, v11, v27
	s_nop 0
	v_max3_f32 v41, v41, v12, v28
	v_max3_f32 v40, v40, v13, v29
	s_nop 0
	v_max3_f32 v41, v41, v14, v30
	v_max3_f32 v40, v40, v15, v31
	s_nop 0
	v_max_f32_e32 v40, v40, v40
	v_max_f32_e32 v41, v41, v41
	v_max_f32_e32 v40, v41, v40
	ds_bpermute_b32 v41, v197, v40
	s_waitcnt lgkmcnt(0)
; template <int KIND> ...
;     ...
;                     for (int j = 0; j < 16; ++j) { mneg[j] -= d; s0[j] -= d; s1[j] -= d; lacc[j] *= alpha; }
; #pragma unroll
;                     for (int dt = 0; dt < NDT; ++dt)
; #pragma unroll
;                         for (int j = 0; j < 16; ++j) o[dt][j] *= alpha;
;                     first = 0;
;                 }
; #pragma unroll
;                 for (int j = 0; j < 16; ++j) s0[j] = __builtin_amdgcn_exp2f(s0[j]);
;                 bf16x8 pf[4];
; #pragma unroll
;                 for (int s = 0; s < 2; ++s) { u32x4 w; w.x = pk2n(s0[8 * s + 0], s0[8 * s + 1]); w.y = pk2n(s0[8 * s + 2], s0[8 * s + 3]); w.z = pk2n(s0[8 * s + 4], s0[8 * s + 5]); w.w = pk2n(s0[8 * s + 6], s0[8 * s + 7]);
;                     pf[s] = __builtin_bit_cast(bf16x8, w); }
;                 __builtin_amdgcn_sched_barrier(0);
; #pragma unroll
;                 for (int s = 0; s < 2; ++s)
; #pragma unroll
;                     for (int dt = 0; dt < NDT; ++dt) {
;                         vfb[s][dt][0] = __builtin_amdgcn_ds_read_tr16_b64_v4i16((LAS s16x4*)(lds + buf * VBUF + voff + (16 * (s + 2)) * VSTR + 64 * dt));
;                         vfb[s][dt][1] = __builtin_amdgcn_ds_read_tr16_b64_v4i16((LAS s16x4*)(lds + buf * VBUF + voff + (16 * (s + 2) + 8) * VSTR + 64 * dt)); }
;                 {
;                     constexpr int NM = 2 * (1 + NDT);
;                     int mi = 0;
; #pragma unroll
;                     for (int s = 0; s < 2; ++s) {
;                         lacc = __builtin_amdgcn_mfma_f32_32x32x16_bf16(ones, pf[s], lacc, 0, 0, 0);
; #pragma unroll
;                         for (int j = (mi * 16) / NM; j < ((mi + 1) * 16) / NM; ++j) s1[j] = __builtin_amdgcn_exp2f(s1[j]);
;                         ++mi;
; #pragma unroll
;                         for (int dt = 0; dt < NDT; ++dt) {
;                             const s16x4 va = vfa[s][dt][0], vb = vfa[s][dt][1];
;                             const bf16x8 vf = {va[0], va[1], va[2], va[3], vb[0], vb[1], vb[2], vb[3]};
;                             o[dt] = __builtin_amdgcn_mfma_f32_32x32x16_bf16(vf, pf[s], o[dt], 0, 0, 0);
; #pragma unroll
;                             for (int j = (mi * 16) / NM; j < ((mi + 1) * 16) / NM; ++j) s1[j] = __builtin_amdgcn_exp2f(s1[j]);
;                             ++mi;
;                         }
;                     }
; #pragma unroll
	v_max_f32_e32 v41, v41, v41
	v_max_f32_e32 v40, v40, v41
	v_sub_f32_e32 v0, v0, v40
	v_sub_f32_e32 v1, v1, v40
	v_sub_f32_e32 v2, v2, v40
	v_sub_f32_e32 v3, v3, v40
	v_sub_f32_e32 v4, v4, v40
	v_sub_f32_e32 v5, v5, v40
	v_sub_f32_e32 v6, v6, v40
	v_sub_f32_e32 v7, v7, v40
	v_sub_f32_e32 v8, v8, v40
	v_sub_f32_e32 v9, v9, v40
	v_sub_f32_e32 v10, v10, v40
	v_sub_f32_e32 v11, v11, v40
	v_sub_f32_e32 v12, v12, v40
	v_sub_f32_e32 v13, v13, v40
	v_sub_f32_e32 v14, v14, v40
	v_sub_f32_e32 v15, v15, v40
	v_exp_f32_e32 v0, v0
	v_exp_f32_e32 v1, v1
	v_exp_f32_e32 v2, v2
	v_exp_f32_e32 v3, v3
	v_exp_f32_e32 v4, v4
	v_exp_f32_e32 v5, v5
	v_exp_f32_e32 v6, v6
	v_exp_f32_e32 v7, v7
	v_exp_f32_e32 v8, v8
	v_exp_f32_e32 v9, v9
	v_exp_f32_e32 v10, v10
	v_exp_f32_e32 v11, v11
	v_exp_f32_e32 v12, v12
	v_exp_f32_e32 v13, v13
	v_exp_f32_e32 v14, v14
	v_exp_f32_e32 v15, v15
	v_sub_f32_e32 v64, 0, v40
	v_sub_f32_e32 v16, v16, v40
	v_sub_f32_e32 v17, v17, v40
	v_sub_f32_e32 v18, v18, v40
	v_sub_f32_e32 v19, v19, v40
	v_sub_f32_e32 v20, v20, v40
	v_sub_f32_e32 v21, v21, v40
	v_sub_f32_e32 v22, v22, v40
	v_sub_f32_e32 v23, v23, v40
	v_sub_f32_e32 v24, v24, v40
	v_mov_b32_e32 v65, v64
	v_mov_b32_e32 v66, v64
	v_mov_b32_e32 v67, v64
	v_mov_b32_e32 v68, v64
	v_mov_b32_e32 v69, v64
	v_mov_b32_e32 v70, v64
	v_mov_b32_e32 v71, v64
	v_mov_b32_e32 v72, v64
	v_mov_b32_e32 v73, v64
	v_mov_b32_e32 v74, v64
	v_mov_b32_e32 v75, v64
	v_mov_b32_e32 v76, v64
	v_mov_b32_e32 v77, v64
	v_mov_b32_e32 v78, v64
	v_mov_b32_e32 v79, v64
	v_cvt_pk_bf16_f32 v0, v0, v1
	v_cvt_pk_bf16_f32 v1, v2, v3
	v_cvt_pk_bf16_f32 v2, v4, v5
	v_cvt_pk_bf16_f32 v3, v6, v7
	v_sub_f32_e32 v160, v25, v40
	v_sub_f32_e32 v161, v26, v40
	v_sub_f32_e32 v162, v27, v40
	v_sub_f32_e32 v163, v28, v40
	v_sub_f32_e32 v164, v29, v40
	v_sub_f32_e32 v165, v30, v40
	v_sub_f32_e32 v166, v31, v40
	v_cvt_pk_bf16_f32 v120, v8, v9
	v_cvt_pk_bf16_f32 v121, v10, v11
	v_cvt_pk_bf16_f32 v122, v12, v13
	v_cvt_pk_bf16_f32 v123, v14, v15
	v_mfma_f32_32x32x16_bf16 v[48:63], v[32:35], v[0:3], 0
	v_mov_b64_e32 v[126:127], s[86:87]
	v_mov_b64_e32 v[124:125], s[84:85]
	v_exp_f32_e32 v167, v16
	s_nop 0
	v_mfma_f32_32x32x16_bf16 v[80:95], v[124:127], v[0:3], 0
	v_exp_f32_e32 v168, v17
	v_exp_f32_e32 v169, v18
	v_exp_f32_e32 v170, v19
	v_mfma_f32_32x32x16_bf16 v[32:47], v[36:39], v[0:3], 0
	v_exp_f32_e32 v171, v20
	v_exp_f32_e32 v172, v21
	v_exp_f32_e32 v173, v22
	v_mfma_f32_32x32x16_bf16 v[80:95], v[124:127], v[120:123], v[80:95]
	v_exp_f32_e32 v174, v23
	v_exp_f32_e32 v175, v24
	v_exp_f32_e32 v176, v160
	v_mfma_f32_32x32x16_bf16 v[16:31], v[112:115], v[0:3], 0
	v_exp_f32_e32 v177, v161
	v_exp_f32_e32 v178, v162
	v_exp_f32_e32 v179, v163
	ds_read_b64_tr_b16 v[112:113], v236 offset:40960
	ds_read_b64_tr_b16 v[114:115], v236 offset:43008
	ds_read_b64_tr_b16 v[160:161], v148 offset:40960
	ds_read_b64_tr_b16 v[162:163], v148 offset:43008
	v_mfma_f32_32x32x16_bf16 v[0:15], v[116:119], v[0:3], 0
	v_exp_f32_e32 v180, v164
	v_exp_f32_e32 v181, v166
	v_exp_f32_e32 v182, v165
	v_mfma_f32_32x32x16_bf16 v[48:63], v[108:111], v[120:123], v[48:63]
	v_cvt_pk_bf16_f32 v116, v167, v168
	v_cvt_pk_bf16_f32 v117, v169, v170
	v_cvt_pk_bf16_f32 v118, v171, v172
	ds_read_b64_tr_b16 v[108:109], v147 offset:40960
	ds_read_b64_tr_b16 v[110:111], v147 offset:43008
	ds_read_b64_tr_b16 v[168:169], v236 offset:45056
	ds_read_b64_tr_b16 v[170:171], v236 offset:47104
	v_mfma_f32_32x32x16_bf16 v[32:47], v[104:107], v[120:123], v[32:47]
	v_cvt_pk_bf16_f32 v119, v173, v174
	v_cvt_pk_bf16_f32 v164, v175, v176
	v_cvt_pk_bf16_f32 v165, v177, v178
	ds_read_b64_tr_b16 v[104:105], v149 offset:40960
	ds_read_b64_tr_b16 v[106:107], v149 offset:43008
	ds_read_b64_tr_b16 v[172:173], v148 offset:45056
	ds_read_b64_tr_b16 v[174:175], v148 offset:47104
	v_mfma_f32_32x32x16_bf16 v[16:31], v[100:103], v[120:123], v[16:31]
	v_cvt_pk_bf16_f32 v166, v179, v180
	v_cvt_pk_bf16_f32 v167, v182, v181
	ds_read_b64_tr_b16 v[100:101], v147 offset:45056
	ds_read_b64_tr_b16 v[102:103], v147 offset:47104
	ds_read_b64_tr_b16 v[176:177], v149 offset:45056
	ds_read_b64_tr_b16 v[178:179], v149 offset:47104
	v_mfma_f32_32x32x16_bf16 v[0:15], v[96:99], v[120:123], v[0:15]
	v_mfma_f32_32x32x16_bf16 v[80:95], v[124:127], v[116:119], v[80:95]
	s_waitcnt lgkmcnt(14)
	v_mfma_f32_32x32x16_bf16 v[48:63], v[112:115], v[116:119], v[48:63]
	s_waitcnt lgkmcnt(10)
	v_mfma_f32_32x32x16_bf16 v[32:47], v[108:111], v[116:119], v[32:47]
	v_mfma_f32_32x32x16_bf16 v[16:31], v[160:163], v[116:119], v[16:31]
	s_waitcnt lgkmcnt(6)
	v_mfma_f32_32x32x16_bf16 v[0:15], v[104:107], v[116:119], v[0:15]
	v_mfma_f32_32x32x16_bf16 v[80:95], v[124:127], v[164:167], v[80:95]
	v_mfma_f32_32x32x16_bf16 v[48:63], v[168:171], v[164:167], v[48:63]
	s_waitcnt lgkmcnt(2)
	v_mfma_f32_32x32x16_bf16 v[32:47], v[100:103], v[164:167], v[32:47]
	v_mfma_f32_32x32x16_bf16 v[16:31], v[172:175], v[164:167], v[16:31]
	s_waitcnt lgkmcnt(0)
	v_mfma_f32_32x32x16_bf16 v[0:15], v[176:179], v[164:167], v[0:15]
	v_lshl_add_u64 v[212:213], s[4:5], 0, v[206:207]
	v_lshl_add_u64 v[214:215], s[4:5], 0, v[208:209]
	s_mov_b32 s16, -3
	v_mov_b32_e32 v248, v245
	v_mov_b32_e32 v249, v244
	v_mov_b32_e32 v250, v243
	s_waitcnt vmcnt(0)
	s_waitcnt lgkmcnt(0)
	s_barrier
	s_branch .LBB0_189
.LBB0_188:
	s_add_i32 s16, s16, 1
	v_add_u32_e32 v250, 64, v250
	v_add_u32_e32 v249, 64, v249
	s_cmp_eq_u32 s3, s16
	v_add_u32_e32 v248, 64, v248
	s_waitcnt vmcnt(0) lgkmcnt(0)
	s_barrier
	s_cbranch_scc1 .LBB0_195

; #define LAS __attribute__((address_space(3)))
; template <int KIND> ...
;     ...
;             if (t + 1 < nt) ATT_LOAD(t + 1);
;             bool active = true;
;             if (KIND == 0 && t < n1) { const int kr = kr_lo + t; active = (kr >= rs_w) && (kr < rs_w + 8); }
;             if (__builtin_amdgcn_readfirstlane((int)active)) {
;                 const int buf = t & 1;
;                 bf16x8 kf[8];
; #pragma unroll
;                 for (int t4 = 0; t4 < 4; ++t4) { kf[2 * t4] = *(const LAS bf16x8*)(lds + buf * KBUF + koff + 32 * t4); kf[2 * t4 + 1] = *(const LAS bf16x8*)(lds + buf * KBUF + koff + 32 * KSTR + 32 * t4); }
;                 __builtin_amdgcn_sched_barrier(0);
;                 f32x16 s0, s1;
; #pragma unroll
;                 for (int t4 = 0; t4 < 4; ++t4) {
;                     s0 = __builtin_amdgcn_mfma_f32_32x32x16_bf16(kf[2 * t4], qf[t4], t4 == 0 ? mneg : s0, 0, 0, 0);
;                     s1 = __builtin_amdgcn_mfma_f32_32x32x16_bf16(kf[2 * t4 + 1], qf[t4], t4 == 0 ? mneg : s1, 0, 0, 0);
;                 }
;                 float ab0[16], ab1[16];
;                 const bool na_lat = (KIND == 0) && (t < n1);
;                 if (na_lat) {
;                     const int bo = boff0 + (kr_lo + t - qr + 7) * 124;
; #pragma unroll
;                     for (int j = 0; j < 16; ++j) {
;                         const int C0 = 8 * (j >> 2) + (j & 3), C1 = 32 + C0;
;                         const float b0 = *(const LAS float*)(lds + bo + 4 * C0), b1 = *(const LAS float*)(lds + bo + 4 * C1);
;                         ab0[j] = ((unsigned)(wb + C0) < 16u) ? b0 : -1e30f;
;                         ab1[j] = ((unsigned)(wb + C1) < 16u) ? b1 : -1e30f;
;                     }
; #pragma unroll
;                     for (int i = 0; i < 8; ++i) { __builtin_amdgcn_sched_group_barrier(0x008, 1, 0); __builtin_amdgcn_sched_group_barrier(0x100, 4, 0); __builtin_amdgcn_sched_group_barrier(0x002, 12, 0); }
;                 }
;                 __builtin_amdgcn_sched_barrier(0);
;                 s16x4 vfa[2][NDT][2], vfb[2][NDT][2];
; #pragma unroll
;                 for (int s = 0; s < 2; ++s)
; #pragma unroll
;                     for (int dt = 0; dt < NDT; ++dt) {
;                         vfa[s][dt][0] = __builtin_amdgcn_ds_read_tr16_b64_v4i16((LAS s16x4*)(lds + buf * VBUF + voff + (16 * s) * VSTR + 64 * dt));
.LBB0_191:
	s_add_i32 s27, s16, 4
	s_and_b32 s27, s27, 1
	s_lshl_b32 s28, s27, 14
	v_add_u32_e32 v100, s28, v235
	v_xor_b32_e32 v144, 32, v100
	v_xor_b32_e32 v145, 64, v100
	v_xor_b32_e32 v146, 0x60, v100
	ds_read_b128 v[96:99], v100
	ds_read_b128 v[160:163], v144
	ds_read_b128 v[164:167], v100 offset:4096
	ds_read_b128 v[168:171], v144 offset:4096
	ds_read_b128 v[172:175], v145
	ds_read_b128 v[218:221], v146
	ds_read_b128 v[176:179], v145 offset:4096
	ds_read_b128 v[230:233], v146 offset:4096
	s_cmp_ge_u32 s17, s26
	s_cbranch_scc1 .Ldf3_noL
	s_cmp_lt_u32 s17, s3
	s_cselect_b32 s35, 0, s3
	s_cselect_b32 s28, s2, s15
	s_lshl_b32 s35, s35, 6
	s_sub_i32 s35, s28, s35
	v_add_u32_e32 v150, s35, v248
	s_movk_i32 s30, 0x1800
	s_and_b32 s29, s17, 1
	s_lshl_b32 s29, s29, 14
	s_add_i32 s29, s29, s18
	v_mad_i64_i32 v[150:151], vcc, v150, s30, v[210:211]
	s_mov_b32 m0, s29
	v_add_u32_e32 v152, s35, v249
	global_load_lds_dwordx4 v[150:151], off
	s_add_i32 m0, s29, 0x1c00
	v_mad_i64_i32 v[152:153], vcc, v152, s30, v[212:213]
	global_load_lds_dwordx4 v[150:151], off offset:1024
	s_add_i32 m0, s29, 0x8000
	v_add_u32_e32 v150, s35, v250
	global_load_lds_dwordx4 v[152:153], off
	v_mad_i64_i32 v[150:151], vcc, v150, s30, v[214:215]
	s_add_i32 m0, s29, 0xa000
	s_nop 0
	global_load_lds_dwordx4 v[150:151], off
.Ldf3_noL:
	s_waitcnt lgkmcnt(7)
	v_mfma_f32_32x32x16_bf16 v[112:127], v[96:99], v[128:131], v[64:79]
	s_lshl_b32 s27, s27, 14
	v_add_u32_e32 v251, s27, v236
	v_xor_b32_e32 v147, 64, v251
	v_xor_b32_e32 v148, 0x80, v251
	v_xor_b32_e32 v149, 0xc0, v251
	s_waitcnt lgkmcnt(5)
	v_mfma_f32_32x32x16_bf16 v[96:111], v[164:167], v[128:131], v[64:79]
	v_mfma_f32_32x32x16_bf16 v[112:127], v[160:163], v[132:135], v[112:127]
	s_waitcnt lgkmcnt(4)
	v_mfma_f32_32x32x16_bf16 v[96:111], v[168:171], v[132:135], v[96:111]
	s_waitcnt lgkmcnt(3)
	v_mfma_f32_32x32x16_bf16 v[112:127], v[172:175], v[136:139], v[112:127]
	s_waitcnt lgkmcnt(1)
	v_mfma_f32_32x32x16_bf16 v[96:111], v[176:179], v[136:139], v[96:111]
	ds_read_b64_tr_b16 v[188:189], v251 offset:32768
	ds_read_b64_tr_b16 v[184:185], v147 offset:32768
	ds_read_b64_tr_b16 v[180:181], v148 offset:32768
	ds_read_b64_tr_b16 v[176:177], v149 offset:32768
	ds_read_b64_tr_b16 v[190:191], v251 offset:34816
	ds_read_b64_tr_b16 v[186:187], v147 offset:34816
	ds_read_b64_tr_b16 v[182:183], v148 offset:34816
	ds_read_b64_tr_b16 v[178:179], v149 offset:34816
	ds_read_b64_tr_b16 v[172:173], v251 offset:36864
	ds_read_b64_tr_b16 v[168:169], v147 offset:36864
	ds_read_b64_tr_b16 v[164:165], v148 offset:36864
	ds_read_b64_tr_b16 v[160:161], v149 offset:36864
	ds_read_b64_tr_b16 v[174:175], v251 offset:38912
	ds_read_b64_tr_b16 v[170:171], v147 offset:38912
	ds_read_b64_tr_b16 v[166:167], v148 offset:38912
	ds_read_b64_tr_b16 v[162:163], v149 offset:38912
	v_mfma_f32_32x32x16_bf16 v[112:127], v[218:221], v[140:143], v[112:127]
	s_waitcnt lgkmcnt(14)
	v_mfma_f32_32x32x16_bf16 v[96:111], v[230:233], v[140:143], v[96:111]
	s_nop 9
	v_max_f32_e32 v218, v127, v127
	s_nop 0
	v_max_f32_e32 v219, v111, v111
	v_max_f32_e32 v218, v219, v218
	v_max3_f32 v219, v218, v112, v96
	v_max3_f32 v218, v218, v113, v97
	s_nop 0
	v_max3_f32 v219, v219, v114, v98
	v_max3_f32 v218, v218, v115, v99
	s_nop 0
	v_max3_f32 v219, v219, v116, v100
	v_max3_f32 v218, v218, v117, v101
	s_nop 0
	v_max3_f32 v219, v219, v118, v102
	v_max3_f32 v218, v218, v119, v103
	s_nop 0
	v_max3_f32 v219, v219, v120, v104
	v_max3_f32 v218, v218, v121, v105
	s_nop 0
	v_max3_f32 v219, v219, v122, v106
	v_max3_f32 v218, v218, v123, v107
	s_nop 0
	v_max3_f32 v219, v219, v124, v108
	v_max3_f32 v218, v218, v125, v109
	s_nop 0
	v_max3_f32 v219, v219, v126, v110
	v_max3_f32 v218, v218, v127, v111
	s_nop 0
	v_max_f32_e32 v218, v218, v218
	v_max_f32_e32 v219, v219, v219
	v_max_f32_e32 v252, v219, v218
	v_cmp_lt_f32_e32 vcc, s31, v252
	s_cbranch_vccz .LBB0_193
	ds_bpermute_b32 v218, v197, v252
	s_waitcnt lgkmcnt(0)
	v_max3_f32 v218, v252, v218, 0
	v_exp_f32_e64 v220, -v218
	v_pk_add_f32 v[112:113], v[112:113], v[218:219] op_sel_hi:[1,0] neg_lo:[0,1] neg_hi:[0,1]
	v_pk_add_f32 v[96:97], v[96:97], v[218:219] op_sel_hi:[1,0] neg_lo:[0,1] neg_hi:[0,1]
	v_pk_add_f32 v[114:115], v[114:115], v[218:219] op_sel_hi:[1,0] neg_lo:[0,1] neg_hi:[0,1]
	v_pk_add_f32 v[98:99], v[98:99], v[218:219] op_sel_hi:[1,0] neg_lo:[0,1] neg_hi:[0,1]
	v_pk_add_f32 v[116:117], v[116:117], v[218:219] op_sel_hi:[1,0] neg_lo:[0,1] neg_hi:[0,1]
	v_pk_add_f32 v[100:101], v[100:101], v[218:219] op_sel_hi:[1,0] neg_lo:[0,1] neg_hi:[0,1]
	v_pk_add_f32 v[118:119], v[118:119], v[218:219] op_sel_hi:[1,0] neg_lo:[0,1] neg_hi:[0,1]
	v_pk_add_f32 v[102:103], v[102:103], v[218:219] op_sel_hi:[1,0] neg_lo:[0,1] neg_hi:[0,1]
	v_pk_add_f32 v[120:121], v[120:121], v[218:219] op_sel_hi:[1,0] neg_lo:[0,1] neg_hi:[0,1]
	v_pk_add_f32 v[104:105], v[104:105], v[218:219] op_sel_hi:[1,0] neg_lo:[0,1] neg_hi:[0,1]
	v_pk_add_f32 v[122:123], v[122:123], v[218:219] op_sel_hi:[1,0] neg_lo:[0,1] neg_hi:[0,1]
	v_pk_add_f32 v[106:107], v[106:107], v[218:219] op_sel_hi:[1,0] neg_lo:[0,1] neg_hi:[0,1]
	v_pk_add_f32 v[124:125], v[124:125], v[218:219] op_sel_hi:[1,0] neg_lo:[0,1] neg_hi:[0,1]
	v_pk_add_f32 v[108:109], v[108:109], v[218:219] op_sel_hi:[1,0] neg_lo:[0,1] neg_hi:[0,1]
	v_pk_add_f32 v[126:127], v[126:127], v[218:219] op_sel_hi:[1,0] neg_lo:[0,1] neg_hi:[0,1]
	v_pk_add_f32 v[110:111], v[110:111], v[218:219] op_sel_hi:[1,0] neg_lo:[0,1] neg_hi:[0,1]
	v_pk_mul_f32 v[94:95], v[94:95], v[220:221] op_sel_hi:[1,0]
	v_pk_mul_f32 v[92:93], v[92:93], v[220:221] op_sel_hi:[1,0]
	v_pk_mul_f32 v[90:91], v[90:91], v[220:221] op_sel_hi:[1,0]
; template <int KIND> ...
;     ...
;                     for (int j = 0; j < 16; ++j) { mneg[j] -= d; s0[j] -= d; s1[j] -= d; lacc[j] *= alpha; }
; #pragma unroll
;                     for (int dt = 0; dt < NDT; ++dt)
; #pragma unroll
;                         for (int j = 0; j < 16; ++j) o[dt][j] *= alpha;
;                     first = 0;
;                 }
; #pragma unroll
;                 for (int j = 0; j < 16; ++j) s0[j] = __builtin_amdgcn_exp2f(s0[j]);
;                 bf16x8 pf[4];
; #pragma unroll
;                 for (int s = 0; s < 2; ++s) { u32x4 w; w.x = pk2n(s0[8 * s + 0], s0[8 * s + 1]); w.y = pk2n(s0[8 * s + 2], s0[8 * s + 3]); w.z = pk2n(s0[8 * s + 4], s0[8 * s + 5]); w.w = pk2n(s0[8 * s + 6], s0[8 * s + 7]);
;                     pf[s] = __builtin_bit_cast(bf16x8, w); }
;                 __builtin_amdgcn_sched_barrier(0);
; #pragma unroll
;                 for (int s = 0; s < 2; ++s)
; #pragma unroll
;                     for (int dt = 0; dt < NDT; ++dt) {
;                         vfb[s][dt][0] = __builtin_amdgcn_ds_read_tr16_b64_v4i16((LAS s16x4*)(lds + buf * VBUF + voff + (16 * (s + 2)) * VSTR + 64 * dt));
;                         vfb[s][dt][1] = __builtin_amdgcn_ds_read_tr16_b64_v4i16((LAS s16x4*)(lds + buf * VBUF + voff + (16 * (s + 2) + 8) * VSTR + 64 * dt)); }
;                 {
;                     constexpr int NM = 2 * (1 + NDT);
;                     int mi = 0;
; #pragma unroll
;                     for (int s = 0; s < 2; ++s) {
;                         lacc = __builtin_amdgcn_mfma_f32_32x32x16_bf16(ones, pf[s], lacc, 0, 0, 0);
; #pragma unroll
;                         for (int j = (mi * 16) / NM; j < ((mi + 1) * 16) / NM; ++j) s1[j] = __builtin_amdgcn_exp2f(s1[j]);
;                         ++mi;
; #pragma unroll
;                         for (int dt = 0; dt < NDT; ++dt) {
;                             const s16x4 va = vfa[s][dt][0], vb = vfa[s][dt][1];
;                             const bf16x8 vf = {va[0], va[1], va[2], va[3], vb[0], vb[1], vb[2], vb[3]};
;                             o[dt] = __builtin_amdgcn_mfma_f32_32x32x16_bf16(vf, pf[s], o[dt], 0, 0, 0);
; #pragma unroll
;                             for (int j = (mi * 16) / NM; j < ((mi + 1) * 16) / NM; ++j) s1[j] = __builtin_amdgcn_exp2f(s1[j]);
;                             ++mi;
;                         }
;                     }
; #pragma unroll
	v_pk_mul_f32 v[88:89], v[88:89], v[220:221] op_sel_hi:[1,0]
	v_pk_mul_f32 v[86:87], v[86:87], v[220:221] op_sel_hi:[1,0]
	v_pk_mul_f32 v[84:85], v[84:85], v[220:221] op_sel_hi:[1,0]
	v_pk_mul_f32 v[82:83], v[82:83], v[220:221] op_sel_hi:[1,0]
	v_pk_mul_f32 v[80:81], v[80:81], v[220:221] op_sel_hi:[1,0]
	v_pk_mul_f32 v[62:63], v[62:63], v[220:221] op_sel_hi:[1,0]
	v_pk_mul_f32 v[60:61], v[60:61], v[220:221] op_sel_hi:[1,0]
	v_pk_mul_f32 v[58:59], v[58:59], v[220:221] op_sel_hi:[1,0]
	v_pk_mul_f32 v[56:57], v[56:57], v[220:221] op_sel_hi:[1,0]
	v_pk_mul_f32 v[54:55], v[54:55], v[220:221] op_sel_hi:[1,0]
	v_pk_mul_f32 v[52:53], v[52:53], v[220:221] op_sel_hi:[1,0]
	v_pk_mul_f32 v[50:51], v[50:51], v[220:221] op_sel_hi:[1,0]
	v_pk_mul_f32 v[48:49], v[48:49], v[220:221] op_sel_hi:[1,0]
	v_pk_mul_f32 v[46:47], v[46:47], v[220:221] op_sel_hi:[1,0]
	v_pk_mul_f32 v[44:45], v[44:45], v[220:221] op_sel_hi:[1,0]
	v_pk_mul_f32 v[42:43], v[42:43], v[220:221] op_sel_hi:[1,0]
	v_pk_mul_f32 v[40:41], v[40:41], v[220:221] op_sel_hi:[1,0]
	v_pk_mul_f32 v[38:39], v[38:39], v[220:221] op_sel_hi:[1,0]
	v_pk_mul_f32 v[36:37], v[36:37], v[220:221] op_sel_hi:[1,0]
	v_pk_mul_f32 v[34:35], v[34:35], v[220:221] op_sel_hi:[1,0]
	v_pk_mul_f32 v[32:33], v[32:33], v[220:221] op_sel_hi:[1,0]
	v_pk_mul_f32 v[30:31], v[30:31], v[220:221] op_sel_hi:[1,0]
	v_pk_mul_f32 v[28:29], v[28:29], v[220:221] op_sel_hi:[1,0]
	v_pk_mul_f32 v[26:27], v[26:27], v[220:221] op_sel_hi:[1,0]
	v_pk_mul_f32 v[24:25], v[24:25], v[220:221] op_sel_hi:[1,0]
	v_pk_mul_f32 v[22:23], v[22:23], v[220:221] op_sel_hi:[1,0]
	v_pk_mul_f32 v[20:21], v[20:21], v[220:221] op_sel_hi:[1,0]
	v_pk_mul_f32 v[18:19], v[18:19], v[220:221] op_sel_hi:[1,0]
	v_pk_mul_f32 v[16:17], v[16:17], v[220:221] op_sel_hi:[1,0]
	v_pk_mul_f32 v[14:15], v[14:15], v[220:221] op_sel_hi:[1,0]
	v_pk_mul_f32 v[12:13], v[12:13], v[220:221] op_sel_hi:[1,0]
	v_pk_mul_f32 v[10:11], v[10:11], v[220:221] op_sel_hi:[1,0]
	v_pk_mul_f32 v[8:9], v[8:9], v[220:221] op_sel_hi:[1,0]
	v_pk_mul_f32 v[6:7], v[6:7], v[220:221] op_sel_hi:[1,0]
	v_pk_mul_f32 v[4:5], v[4:5], v[220:221] op_sel_hi:[1,0]
	v_pk_mul_f32 v[2:3], v[2:3], v[220:221] op_sel_hi:[1,0]
	v_pk_mul_f32 v[0:1], v[0:1], v[220:221] op_sel_hi:[1,0]
	v_sub_f32_e32 v79, v79, v218
	v_sub_f32_e32 v78, v78, v218
	v_sub_f32_e32 v77, v77, v218
	v_sub_f32_e32 v76, v76, v218
	v_sub_f32_e32 v75, v75, v218
	v_sub_f32_e32 v74, v74, v218
	v_sub_f32_e32 v73, v73, v218
	v_sub_f32_e32 v72, v72, v218
	v_sub_f32_e32 v71, v71, v218
	v_sub_f32_e32 v70, v70, v218
	v_sub_f32_e32 v69, v69, v218
	v_sub_f32_e32 v68, v68, v218
	v_sub_f32_e32 v67, v67, v218
	v_sub_f32_e32 v66, v66, v218
	v_sub_f32_e32 v65, v65, v218
	v_sub_f32_e32 v64, v64, v218
.LBB0_193:
	v_exp_f32_e32 v112, v112
	v_exp_f32_e32 v113, v113
	v_exp_f32_e32 v114, v114
	v_exp_f32_e32 v115, v115
	v_exp_f32_e32 v116, v116
	v_exp_f32_e32 v117, v117
	v_exp_f32_e32 v118, v118
	v_exp_f32_e32 v119, v119
	v_exp_f32_e32 v120, v120
	v_exp_f32_e32 v121, v121
	v_exp_f32_e32 v122, v122
	v_exp_f32_e32 v123, v123
	v_exp_f32_e32 v124, v124
	v_exp_f32_e32 v125, v125
	v_exp_f32_e32 v126, v126
	v_exp_f32_e32 v127, v127
	v_cvt_pk_bf16_f32 v112, v112, v113
	v_cvt_pk_bf16_f32 v113, v114, v115
	v_cvt_pk_bf16_f32 v114, v116, v117
	v_cvt_pk_bf16_f32 v115, v118, v119
	v_cvt_pk_bf16_f32 v116, v120, v121
	v_cvt_pk_bf16_f32 v117, v122, v123
	v_cvt_pk_bf16_f32 v118, v124, v125
	v_cvt_pk_bf16_f32 v119, v126, v127
	s_waitcnt lgkmcnt(11)
	v_mfma_f32_32x32x16_bf16 v[48:63], v[188:191], v[112:115], v[48:63]
	v_mov_b64_e32 v[122:123], s[86:87]
	v_mov_b64_e32 v[120:121], s[84:85]
	v_exp_f32_e32 v124, v96
	s_nop 0
	v_mfma_f32_32x32x16_bf16 v[80:95], v[120:123], v[112:115], v[80:95]
	v_exp_f32_e32 v125, v97
	v_exp_f32_e32 v98, v98
	v_exp_f32_e32 v99, v99
	ds_read_b64_tr_b16 v[96:97], v251 offset:40960
	s_waitcnt lgkmcnt(11)
	v_mfma_f32_32x32x16_bf16 v[32:47], v[184:187], v[112:115], v[32:47]
	v_exp_f32_e32 v126, v100
	v_exp_f32_e32 v127, v101
	v_exp_f32_e32 v184, v102
	s_waitcnt lgkmcnt(10)
	v_mfma_f32_32x32x16_bf16 v[16:31], v[180:183], v[112:115], v[16:31]
	v_exp_f32_e32 v103, v103
	v_exp_f32_e32 v185, v104
	v_exp_f32_e32 v180, v105
	ds_read_b64_tr_b16 v[104:105], v147 offset:40960
	s_waitcnt lgkmcnt(10)
	v_mfma_f32_32x32x16_bf16 v[0:15], v[176:179], v[112:115], v[0:15]
	v_exp_f32_e32 v181, v106
	v_exp_f32_e32 v182, v107
	v_exp_f32_e32 v114, v108
	ds_read_b64_tr_b16 v[106:107], v147 offset:43008
	ds_read_b64_tr_b16 v[178:179], v149 offset:47104
	v_mfma_f32_32x32x16_bf16 v[80:95], v[120:123], v[116:119], v[80:95]
	v_exp_f32_e32 v115, v109
	v_exp_f32_e32 v176, v110
	v_exp_f32_e32 v177, v111
	ds_read_b64_tr_b16 v[108:109], v148 offset:40960
	ds_read_b64_tr_b16 v[110:111], v148 offset:43008
	s_waitcnt lgkmcnt(9)
	v_mfma_f32_32x32x16_bf16 v[48:63], v[172:175], v[116:119], v[48:63]
	v_cvt_pk_bf16_f32 v100, v124, v125
	v_cvt_pk_bf16_f32 v101, v98, v99
	v_cvt_pk_bf16_f32 v102, v126, v127
	ds_read_b64_tr_b16 v[98:99], v251 offset:43008
	ds_read_b64_tr_b16 v[124:125], v149 offset:40960
	ds_read_b64_tr_b16 v[126:127], v149 offset:43008
	ds_read_b64_tr_b16 v[172:173], v148 offset:45056
	s_waitcnt lgkmcnt(12)
	v_mfma_f32_32x32x16_bf16 v[32:47], v[168:171], v[116:119], v[32:47]
	v_cvt_pk_bf16_f32 v103, v184, v103
	v_cvt_pk_bf16_f32 v112, v185, v180
	v_cvt_pk_bf16_f32 v113, v181, v182
	ds_read_b64_tr_b16 v[168:169], v251 offset:45056
	ds_read_b64_tr_b16 v[170:171], v251 offset:47104
	ds_read_b64_tr_b16 v[174:175], v148 offset:47104
	s_waitcnt lgkmcnt(14)
	v_mfma_f32_32x32x16_bf16 v[16:31], v[164:167], v[116:119], v[16:31]
	v_cvt_pk_bf16_f32 v114, v114, v115
	v_cvt_pk_bf16_f32 v115, v176, v177
	ds_read_b64_tr_b16 v[164:165], v147 offset:45056
	ds_read_b64_tr_b16 v[166:167], v147 offset:47104
	ds_read_b64_tr_b16 v[176:177], v149 offset:45056
	s_waitcnt lgkmcnt(14)
	v_mfma_f32_32x32x16_bf16 v[0:15], v[160:163], v[116:119], v[0:15]
	v_mfma_f32_32x32x16_bf16 v[80:95], v[120:123], v[100:103], v[80:95]
	s_waitcnt lgkmcnt(9)
	v_mfma_f32_32x32x16_bf16 v[48:63], v[96:99], v[100:103], v[48:63]
	v_mfma_f32_32x32x16_bf16 v[32:47], v[104:107], v[100:103], v[32:47]
	v_mfma_f32_32x32x16_bf16 v[16:31], v[108:111], v[100:103], v[16:31]
	s_waitcnt lgkmcnt(7)
	v_mfma_f32_32x32x16_bf16 v[0:15], v[124:127], v[100:103], v[0:15]
	v_mfma_f32_32x32x16_bf16 v[80:95], v[120:123], v[112:115], v[80:95]
	s_waitcnt lgkmcnt(4)
	v_mfma_f32_32x32x16_bf16 v[48:63], v[168:171], v[112:115], v[48:63]
	s_waitcnt lgkmcnt(1)
	v_mfma_f32_32x32x16_bf16 v[32:47], v[164:167], v[112:115], v[32:47]
	v_mfma_f32_32x32x16_bf16 v[16:31], v[172:175], v[112:115], v[16:31]
	s_waitcnt lgkmcnt(0)
	v_mfma_f32_32x32x16_bf16 v[0:15], v[176:179], v[112:115], v[0:15]
	s_branch .LBB0_188

; __device__ __forceinline__ float wave_sum(float v) {
; #pragma unroll
;     for (int o = 1; o < 64; o <<= 1) v += __shfl_xor(v, o);
;     return v;
; }
; template <int KIND> ...
;     ...
;     if (KIND == 2) { const float s01 = wave_sum(lam[lane] * lam[64 + lane]), s23 = wave_sum(lam[128 + lane] * lam[192 + lane]);
.LBB0_201:
	v_xor_b32_e32 v226, 1, v216
	v_xor_b32_e32 v246, 2, v216
	v_xor_b32_e32 v247, 4, v216
